# mixer work queue: next pair index prefetched one item ahead by thread 0 (returning atomic parked in a spare VGPR), LDS hand-off via ds ops instead of flat ops
# baseline (speedup 1.0000x reference)
.LBB0_127:
	v_readlane_b32 s0, v255, 40
	v_readlane_b32 s1, v255, 41
	s_mov_b32 s6, s0
	s_lshl_b32 s0, s0, 2
	v_readlane_b32 s1, v254, 41
	s_add_u32 s66, s1, s0
	v_readlane_b32 s0, v254, 42
	s_addc_u32 s67, s0, 0
	s_lshl_b32 s0, s6, 2
	v_writelane_b32 v255, s0, 47
	s_lshl_b32 s0, s6, 1
	s_mov_b32 s1, s21
	v_writelane_b32 v255, s0, 48
	s_lshl_b32 s20, s6, 7
	v_readlane_b32 s36, v254, 53
	v_writelane_b32 v255, s1, 49
	s_lshl_b32 s0, s6, 3
	v_writelane_b32 v255, s0, 50
	s_lshl_b64 s[0:1], s[20:21], 2
	v_readlane_b32 s48, v255, 1
	v_readlane_b32 s49, v255, 2
	s_add_u32 s0, s48, s0
	s_addc_u32 s1, s49, s1
	v_readlane_b32 s47, v255, 0
	v_readlane_b32 s50, v255, 3
	v_readlane_b32 s51, v255, 4
	v_writelane_b32 v255, s0, 51
	v_mov_b32_e32 v0, v137
	v_readlane_b32 s37, v254, 54
	v_writelane_b32 v255, s1, 52
	v_readfirstlane_b32 s0, v0
	v_cmp_eq_u32_e64 s[62:63], 0, v0
	s_ashr_i32 s9, s0, 8
	v_and_b32_e32 v161, 63, v0
	v_writelane_b32 v255, s62, 53
	v_bfe_u32 v201, v0, 6, 2
	s_mul_i32 s11, s9, 0x12000
	v_writelane_b32 v255, s63, 54
	v_readlane_b32 s38, v254, 55
	v_readlane_b32 s39, v254, 56
	v_readlane_b32 s40, v254, 57
	v_readlane_b32 s41, v254, 58
	v_readlane_b32 s42, v254, 59
	v_readlane_b32 s43, v254, 60
	v_readlane_b32 s44, v254, 61
	v_readlane_b32 s45, v254, 62
	v_readlane_b32 s46, v254, 63
	s_and_saveexec_b64 s[0:1], s[62:63]
	v_mov_b32_e32 v243, 1
	global_atomic_add v242, v1, v243, s[66:67] sc0
	s_or_b64 exec, exec, s[0:1]
	s_branch .LBB0_130

.LBB0_130:
	s_waitcnt vmcnt(0) lgkmcnt(0)
	s_barrier
	s_and_saveexec_b64 s[0:1], s[62:63]
	s_cbranch_execz .LBB0_134
	ds_write_b32 v162, v242
	v_mov_b32_e32 v243, 1
	global_atomic_add v242, v1, v243, s[66:67] sc0
	s_waitcnt lgkmcnt(0)
.LBB0_134:
	s_or_b64 exec, exec, s[0:1]
	s_barrier
	ds_read_b32 v0, v162
	s_mov_b64 s[0:1], -1
	s_waitcnt lgkmcnt(0)
	v_lshl_add_u32 v0, v0, 1, s9
	s_nop 0
	v_readfirstlane_b32 s12, v0
	s_cmpk_gt_i32 s12, 0x57f
	s_cbranch_scc1 .LBB0_129
	s_cmpk_gt_i32 s12, 0xff
	s_cbranch_scc0 .LBB0_318
	s_cmpk_gt_u32 s12, 0x17f
	s_cbranch_scc0 .LBB0_288
	s_cmpk_gt_u32 s12, 0x1ff
	s_cbranch_scc0 .LBB0_277
	s_cmpk_gt_u32 s12, 0x27f
	s_cbranch_scc0 .LBB0_220
	s_cmpk_gt_u32 s12, 0x37f
	s_cbranch_scc0 .LBB0_199
	s_cmpk_gt_u32 s12, 0x47f
	s_cbranch_scc0 .LBB0_156
	s_mov_b64 s[0:1], 0
	s_add_u32 s0, s94, s0
	s_addc_u32 s1, s95, s1
	s_mov_b64 s[22:23], 0
	s_lshl_b32 s6, s12, 4
	s_and_b32 s13, s6, 0x7fffff00
	s_add_i32 s22, s13, 0xffffb800
	s_add_u32 s26, s0, 0x8748000
	s_addc_u32 s27, s1, 0
	s_lshl_b32 s13, s12, 6
	v_mov_b32_e32 v22, v161
	s_and_b32 s13, s13, 0xc0
	v_readfirstlane_b32 s8, v201
	v_and_b32_e32 v26, 15, v22
	s_or_b32 s13, s13, s22
	s_lshl_b32 s36, s8, 4
	v_or_b32_e32 v0, s13, v26
	v_ashrrev_i32_e32 v53, 4, v22
	v_add_u32_e32 v50, s36, v0
	v_mov_b64_e32 v[2:3], s[26:27]
	s_movk_i32 s13, 0x1a20
	s_and_b32 s14, s6, 0xc0
	v_mad_i64_i32 v[2:3], s[34:35], v50, s13, v[2:3]
	s_lshl_b32 s20, s14, 1
	v_lshlrev_b32_e32 v4, 3, v53
	v_lshl_add_u64 v[2:3], v[2:3], 0, s[20:21]
	v_ashrrev_i32_e32 v5, 31, v4
	v_lshl_add_u64 v[2:3], v[4:5], 1, v[2:3]
	global_load_dwordx4 v[6:9], v[2:3], off offset:3072
	s_nop 0
	global_load_dwordx4 v[2:5], v[2:3], off offset:3136
	s_mul_i32 s13, s22, 0x1a20
	s_mul_hi_u32 s6, s22, 0x1a20
	s_add_u32 s13, s26, s13
	s_addc_u32 s6, s27, s6
	s_add_u32 s38, s13, s20
	s_addc_u32 s39, s6, 0
	s_mov_b32 s23, s21
	s_add_u32 s6, s38, 0xe00
	s_addc_u32 s13, s39, 0
	s_lshl_b64 s[22:23], s[22:23], 9
	v_ashrrev_i32_e32 v12, 3, v22
	s_add_u32 s19, s0, s22
	v_add_u32_e32 v0, s36, v12
	s_addc_u32 s22, s1, s23
	s_lshl_b32 s14, s14, 6
	v_and_b32_e32 v13, 2, v12
	v_lshrrev_b32_e32 v10, 1, v0
	s_add_u32 s44, s19, s14
	v_and_or_b32 v10, v10, 12, v13
	s_movk_i32 s16, 0xd10
	s_addc_u32 s49, s22, 0
	v_lshrrev_b32_e32 v10, 1, v10
	v_mad_i64_i32 v[46:47], s[22:23], v0, s16, 0
	s_add_u32 s14, s44, 0xb478000
	v_bitop3_b32 v58, v10, v22, 7 bitop3:0x78
	v_lshlrev_b64 v[34:35], 1, v[46:47]
	s_addc_u32 s19, s49, 0
	v_lshl_add_u64 v[10:11], s[38:39], 0, v[34:35]
	v_lshlrev_b32_e32 v0, 4, v58
	s_lshl_b32 s22, s8, 11
	s_lshl_b32 s26, s8, 1
	v_lshl_add_u64 v[10:11], v[10:11], 0, v[0:1]
	s_mov_b64 s[34:35], 0xe00
	s_add_i32 s48, s11, s22
	v_lshl_add_u64 v[10:11], v[10:11], 0, s[34:35]
	s_mov_b32 m0, s48
	s_or_b32 s37, s26, 1
	s_barrier
	global_load_lds_dwordx4 v[10:11], off
	v_lshl_add_u32 v10, s37, 3, v12
	v_lshrrev_b32_e32 v11, 1, v10
	v_and_or_b32 v11, v11, 12, v13
	v_mad_i64_i32 v[48:49], s[22:23], v10, s16, 0
	v_lshrrev_b32_e32 v11, 1, v11
	s_lshl_b32 s22, s37, 10
	v_bitop3_b32 v60, v11, v22, 7 bitop3:0x78
	v_lshlrev_b64 v[36:37], 1, v[48:49]
	s_add_i32 s45, s11, s22
	s_lshr_b32 s22, s8, 31
	v_lshl_add_u64 v[10:11], s[38:39], 0, v[36:37]
	v_lshlrev_b32_e32 v38, 4, v60
	v_mov_b32_e32 v39, v1
	s_add_i32 s22, s8, s22
	s_bfe_i32 s8, s8, 0x1001e
	v_lshl_add_u64 v[10:11], v[10:11], 0, v[38:39]
	s_lshr_b32 s8, s8, 30
	v_lshl_add_u64 v[10:11], v[10:11], 0, s[34:35]
	s_ashr_i32 s34, s22, 1
	s_add_i32 s22, s26, s8
	s_and_b32 s22, s22, 0x7ffffc
	s_ashr_i32 s35, s34, 31
	s_sub_i32 s22, s26, s22
	s_lshl_b64 s[40:41], s[34:35], 14
	s_add_u32 s26, s14, s40
	s_addc_u32 s27, s19, s41
	s_lshl_b32 s22, s22, 9
	s_ashr_i32 s23, s22, 31
	s_lshl_b64 s[22:23], s[22:23], 1
	s_add_u32 s26, s26, s22
	s_addc_u32 s27, s27, s23
	s_add_i32 s8, s37, s8
	s_mov_b32 m0, s45
	s_ashr_i32 s36, s8, 2
	s_and_b32 s8, s8, 0x7ffffc
	global_load_lds_dwordx4 v[10:11], off
	v_lshlrev_b32_e32 v10, 3, v22
	s_sub_i32 s8, s37, s8
	s_ashr_i32 s37, s36, 31
	v_ashrrev_i32_e32 v11, 31, v10
	s_add_i32 s46, s48, 0x2000
	s_lshl_b64 s[42:43], s[36:37], 14
	v_lshlrev_b64 v[56:57], 1, v[10:11]
	s_add_u32 s47, s14, s42
	v_lshl_add_u64 v[10:11], s[26:27], 0, v[56:57]
	s_addc_u32 s53, s19, s43
	s_lshl_b32 s26, s8, 9
	s_ashr_i32 s27, s26, 31
	s_lshl_b64 s[26:27], s[26:27], 1
	s_add_u32 s52, s47, s26
	s_mov_b32 m0, s46
	s_addc_u32 s53, s53, s27
	s_add_i32 s47, s45, 0x2000
	global_load_lds_dwordx4 v[10:11], off
	v_lshl_add_u64 v[10:11], s[52:53], 0, v[56:57]
	s_mov_b32 m0, s47
	v_lshrrev_b32_e32 v14, 1, v22
	global_load_lds_dwordx4 v[10:11], off
	v_lshlrev_b32_e32 v10, 1, v22
	v_and_b32_e32 v11, 3, v22
	v_and_or_b32 v10, v10, 24, v11
	v_bitop3_b32 v11, v14, v53, 7 bitop3:0x6c
	v_add_u32_e32 v16, 4, v53
	v_lshlrev_b32_e32 v11, 4, v11
	v_lshl_add_u32 v15, v10, 7, s11
	v_bitop3_b32 v14, v14, v16, 7 bitop3:0x6c
	v_add_u32_e32 v70, v15, v11
	v_lshlrev_b32_e32 v14, 4, v14
	s_waitcnt vmcnt(0)
	s_waitcnt vmcnt(0) lgkmcnt(0)
	s_barrier
	ds_read_b128 v[10:13], v70
	v_add_u32_e32 v71, v15, v14
	ds_read_b128 v[14:17], v70 offset:512
	ds_read_b128 v[18:21], v71
	v_and_b32_e32 v27, -16, v22
	ds_read_b128 v[22:25], v71 offset:512
	s_waitcnt lgkmcnt(3)
	v_mfma_f32_16x16x32_bf16 v[10:13], v[10:13], v[6:9], 0
	s_mov_b32 s8, 0xff800000
	s_waitcnt lgkmcnt(2)
	v_mfma_f32_16x16x32_bf16 v[14:17], v[14:17], v[6:9], 0
	s_waitcnt lgkmcnt(1)
	v_mfma_f32_16x16x32_bf16 v[10:13], v[18:21], v[2:5], v[10:13]
	v_lshlrev_b32_e32 v18, 6, v26
	v_add_u32_e32 v19, s11, v27
	v_add_u32_e32 v51, v19, v18
	s_waitcnt lgkmcnt(0)
	v_mfma_f32_16x16x32_bf16 v[14:17], v[22:25], v[2:5], v[14:17]
	ds_read_b128 v[18:21], v51 offset:8192
	ds_read_b128 v[26:29], v51 offset:9216
	ds_read_b128 v[30:33], v51 offset:10240
	ds_read_b128 v[76:79], v51 offset:11264
	v_mul_f32_e32 v22, 0x3e38aa3b, v10
	v_mul_f32_e32 v24, 0x3e38aa3b, v11
	v_mul_f32_e32 v40, 0x3e38aa3b, v12
	s_nop 0
	v_mul_f32_e32 v41, 0x3e38aa3b, v16
	v_mul_f32_e32 v42, 0x3e38aa3b, v13
	v_mul_f32_e32 v43, 0x3e38aa3b, v17
	v_mul_f32_e32 v23, 0x3e38aa3b, v14
	v_mul_f32_e32 v25, 0x3e38aa3b, v15
	v_max_f32_e32 v22, v22, v24
	v_max_f32_e32 v24, v40, v42
	v_max_f32_e32 v40, v41, v43
	v_max3_f32 v23, v23, v25, v40
	v_max3_f32 v22, v22, v24, v23
	v_mov_b32_e32 v23, v22
	s_nop 1
	v_permlane16_swap_b32_e32 v22, v23
	v_max_f32_e32 v23, v23, v23
	v_max_f32_e32 v22, v22, v22
	v_max_f32_e32 v22, v22, v23
	v_mov_b32_e32 v23, v22
	s_nop 1
	v_permlane32_swap_b32_e32 v22, v23
	v_max3_f32 v52, v22, v23, s8
	s_mov_b32 s8, 0x3e38aa3b
	v_sub_f32_e32 v22, 0xff800000, v52
	v_fma_f32 v10, v10, s8, -v52
	v_exp_f32_e32 v55, v10
	v_fma_f32 v10, v11, s8, -v52
	v_exp_f32_e32 v11, v22
	v_exp_f32_e32 v59, v10
	v_fma_f32 v10, v12, s8, -v52
	v_exp_f32_e32 v61, v10
	v_fma_f32 v10, v13, s8, -v52
	v_cmp_neq_f32_e32 vcc, 1.0, v11
	v_exp_f32_e32 v64, v10
	v_fma_f32 v10, v14, s8, -v52
	s_cmp_lg_u64 vcc, 0
	v_exp_f32_e32 v65, v10
	v_fma_f32 v10, v15, s8, -v52
	v_mul_f32_e32 v68, 0, v11
	s_cselect_b64 vcc, -1, 0
	s_add_u32 s38, s38, 0x69600
	v_exp_f32_e32 v66, v10
	v_fma_f32 v10, v16, s8, -v52
	v_cndmask_b32_e32 v80, 0, v68, vcc
	s_addc_u32 s39, s39, 0
	v_exp_f32_e32 v67, v10
	v_fma_f32 v10, v17, s8, -v52
	v_mov_b32_e32 v81, v80
	v_mov_b32_e32 v82, v80
	v_mov_b32_e32 v83, v80
	s_add_u32 s8, s44, 0xb480000
	v_exp_f32_e32 v69, v10
	s_nop 1
	v_cvt_pk_bf16_f32 v84, v55, v59
	v_cvt_pk_bf16_f32 v85, v61, v64
	v_cvt_pk_bf16_f32 v86, v65, v66
	v_cvt_pk_bf16_f32 v87, v67, v69
	s_nop 1
	s_addc_u32 s49, s49, 0
	s_waitcnt lgkmcnt(3)
	v_mfma_f32_16x16x32_bf16 v[14:17], v[18:21], v[84:87], v[80:83]
	v_lshl_add_u64 v[18:19], s[38:39], 0, v[34:35]
	s_add_i32 s44, s48, 0x4000
	v_lshl_add_u64 v[18:19], v[18:19], 0, v[0:1]
	s_mov_b32 m0, s44
	s_waitcnt lgkmcnt(2)
	v_mfma_f32_16x16x32_bf16 v[10:13], v[26:29], v[84:87], v[80:83]
	global_load_lds_dwordx4 v[18:19], off
	v_lshl_add_u64 v[18:19], s[38:39], 0, v[36:37]
	s_add_i32 s38, s45, 0x4000
	s_add_u32 s39, s8, s40
	s_addc_u32 s41, s49, s41
	s_add_u32 s40, s39, s22
	s_addc_u32 s41, s41, s23
	s_add_i32 s39, s48, 0x6000
	v_lshl_add_u64 v[18:19], v[18:19], 0, v[38:39]
	s_mov_b32 m0, s38
	s_add_u32 s8, s8, s42
	global_load_lds_dwordx4 v[18:19], off
	v_lshl_add_u64 v[18:19], s[40:41], 0, v[56:57]
	s_addc_u32 s41, s49, s43
	s_add_u32 s40, s8, s26
	s_mov_b32 m0, s39
	s_addc_u32 s41, s41, s27
	global_load_lds_dwordx4 v[18:19], off
	v_lshl_add_u64 v[18:19], s[40:41], 0, v[56:57]
	s_add_i32 s40, s45, 0x6000
	s_mov_b32 m0, s40
	s_waitcnt lgkmcnt(0)
	v_mfma_f32_16x16x32_bf16 v[34:37], v[30:33], v[84:87], v[80:83]
	global_load_lds_dwordx4 v[18:19], off
	ds_read_b128 v[18:21], v70 offset:4096
	ds_read_b128 v[22:25], v70 offset:4608
	ds_read_b128 v[26:29], v71 offset:4096
	ds_read_b128 v[30:33], v71 offset:4608
	s_waitcnt lgkmcnt(0)
	v_mfma_f32_16x16x32_bf16 v[38:41], v[22:25], v[6:9], 0
	v_mfma_f32_16x16x32_bf16 v[18:21], v[18:21], v[6:9], 0
	v_mfma_f32_16x16x32_bf16 v[30:33], v[30:33], v[2:5], v[38:41]
	v_mfma_f32_16x16x32_bf16 v[18:21], v[26:29], v[2:5], v[18:21]
	ds_read_b128 v[22:25], v51 offset:12288
	ds_read_b128 v[26:29], v51 offset:13312
	s_nop 4
	v_mul_f32_e32 v44, 0x3e38aa3b, v32
	v_mul_f32_e32 v45, 0x3e38aa3b, v33
	v_mul_f32_e32 v42, 0x3e38aa3b, v30
	v_mul_f32_e32 v54, 0x3e38aa3b, v18
	v_mul_f32_e32 v62, 0x3e38aa3b, v19
	v_mul_f32_e32 v43, 0x3e38aa3b, v31
	v_mul_f32_e32 v63, 0x3e38aa3b, v20
	v_mul_f32_e32 v75, 0x3e38aa3b, v21
	v_max_f32_e32 v19, v44, v45
	v_max_f32_e32 v0, v54, v62
	v_max_f32_e32 v18, v63, v75
	v_max3_f32 v19, v42, v43, v19
	v_max3_f32 v0, v0, v18, v19
	v_mov_b32_e32 v18, v0
	s_nop 1
	v_permlane16_swap_b32_e32 v0, v18
	v_max_f32_e32 v18, v18, v18
	v_max_f32_e32 v0, v0, v0
	v_max_f32_e32 v0, v0, v18
	v_mov_b32_e32 v18, v0
	s_nop 1
	v_permlane32_swap_b32_e32 v0, v18
	v_max3_f32 v0, v52, v0, v18
	v_sub_f32_e32 v18, v52, v0
	v_exp_f32_e32 v52, v18
	ds_read_b128 v[38:41], v51 offset:14336
	ds_read_b128 v[18:21], v51 offset:15360
	v_mfma_f32_16x16x32_bf16 v[30:33], v[76:79], v[84:87], v[80:83]
	v_cmp_neq_f32_e32 vcc, 1.0, v52
	s_cbranch_vccz .LBB0_143
	v_pk_mul_f32 v[16:17], v[16:17], v[52:53] op_sel_hi:[1,0]
	v_pk_mul_f32 v[14:15], v[14:15], v[52:53] op_sel_hi:[1,0]
	v_pk_mul_f32 v[12:13], v[12:13], v[52:53] op_sel_hi:[1,0]
	v_pk_mul_f32 v[10:11], v[10:11], v[52:53] op_sel_hi:[1,0]
	v_pk_mul_f32 v[36:37], v[36:37], v[52:53] op_sel_hi:[1,0]
	v_pk_mul_f32 v[34:35], v[34:35], v[52:53] op_sel_hi:[1,0]
	v_pk_mul_f32 v[32:33], v[32:33], v[52:53] op_sel_hi:[1,0]
	v_pk_mul_f32 v[30:31], v[30:31], v[52:53] op_sel_hi:[1,0]
